# mixb PV: dropped the ten per-task workgroup barriers around the V-transpose staging buffer, which is private to each wave (its own lgkmcnt(0) orders the LDS writes before the reads)
# speedup vs baseline: 1.0310x; 1.0067x over previous
; DI float ex2(float x) { return __builtin_amdgcn_exp2f(x); }
; DI void phase_mixb(const Prm& p, unsigned char* smem_raw, int S, int lgS, int& base) {
;     ...
;         mx = fmaxf(mx, s);
;       }
;     mx = fmaxf(mx, __shfl_xor(mx, 32));
;     float sum = 0.f;
; #pragma unroll
;     for (int tt = 0; tt < 5; ++tt)
; #pragma unroll
;       for (int r = 0; r < 16; ++r) {
;         const float pv = ex2(sc[tt][r] - mx);
;         sum += pv;
;         sc[tt][r] = pv;
;       }
;     sum += __shfl_xor(sum, 32);
.LBB0_1997:
	s_or_b64 exec, exec, s[2:3]
	s_mov_b32 s2, 0xf149f2ca
	v_max3_f32 v2, v84, s2, v83
	v_max3_f32 v2, v2, v86, v67
	v_max3_f32 v2, v2, v69, v68
	v_max3_f32 v2, v2, v71, v70
	v_max3_f32 v2, v2, v73, v72
	v_max3_f32 v2, v2, v75, v74
	v_max3_f32 v2, v2, v77, v76
	v_max3_f32 v2, v2, v79, v78
	v_max3_f32 v2, v2, v81, v80
	v_max3_f32 v2, v2, v51, v50
	v_max3_f32 v2, v2, v53, v52
	v_max3_f32 v2, v2, v55, v54
	v_max3_f32 v2, v2, v57, v56
	v_max3_f32 v2, v2, v59, v58
	v_max3_f32 v2, v2, v61, v60
	v_max3_f32 v2, v2, v63, v62
	v_max3_f32 v2, v2, v65, v64
	v_max3_f32 v2, v2, v35, v34
	v_max3_f32 v2, v2, v87, v88
	v_max3_f32 v2, v2, v89, v39
	v_max3_f32 v2, v2, v41, v40
	v_max3_f32 v2, v2, v43, v42
	v_max3_f32 v2, v2, v45, v44
	v_max3_f32 v2, v2, v47, v46
	v_max3_f32 v2, v2, v49, v48
	v_max3_f32 v2, v2, v19, v18
	v_max3_f32 v2, v2, v21, v20
	v_max3_f32 v2, v2, v23, v22
	v_max3_f32 v2, v2, v25, v24
	v_max3_f32 v2, v2, v27, v26
	v_max3_f32 v2, v2, v29, v28
	v_max3_f32 v2, v2, v31, v30
	v_max3_f32 v2, v2, v33, v32
	v_max3_f32 v2, v2, v156, v91
	v_max3_f32 v2, v2, v158, v157
	v_max3_f32 v2, v2, v160, v159
	v_max3_f32 v2, v2, v162, v161
	v_max3_f32 v2, v2, v11, v10
	v_max3_f32 v2, v2, v13, v12
	v_max3_f32 v2, v2, v15, v14
	ds_bpermute_b32 v3, v106, v2
	v_readlane_b32 s36, v253, 24
	v_readlane_b32 s38, v253, 26
	v_readlane_b32 s39, v253, 27
	s_movk_i32 s4, 0x900
	s_waitcnt lgkmcnt(0)
	v_max_f32_e32 v3, v3, v3
	v_max_f32_e32 v36, v2, v3
	v_sub_f32_e32 v2, v84, v36
	v_exp_f32_e32 v2, v2
	v_sub_f32_e32 v3, v83, v36
	v_exp_f32_e32 v3, v3
	v_sub_f32_e32 v17, v73, v36
	v_add_f32_e32 v4, 0, v2
	v_exp_f32_e32 v148, v17
	v_add_f32_e32 v5, v3, v4
	v_sub_f32_e32 v4, v86, v36
	v_exp_f32_e32 v4, v4
	v_sub_f32_e32 v17, v72, v36
	v_exp_f32_e32 v149, v17
	v_sub_f32_e32 v17, v75, v36
	v_add_f32_e32 v6, v4, v5
	v_sub_f32_e32 v5, v67, v36
	v_exp_f32_e32 v5, v5
	v_exp_f32_e32 v150, v17
	v_sub_f32_e32 v17, v74, v36
	v_exp_f32_e32 v151, v17
	v_add_f32_e32 v7, v5, v6
	v_sub_f32_e32 v6, v69, v36
	v_exp_f32_e32 v6, v6
	v_sub_f32_e32 v17, v77, v36
	v_exp_f32_e32 v152, v17
	v_sub_f32_e32 v17, v76, v36
	v_add_f32_e32 v8, v6, v7
	v_sub_f32_e32 v7, v68, v36
	v_exp_f32_e32 v7, v7
	v_exp_f32_e32 v153, v17
	v_sub_f32_e32 v17, v79, v36
	v_exp_f32_e32 v154, v17
	v_add_f32_e32 v9, v7, v8
	v_sub_f32_e32 v8, v71, v36
	v_exp_f32_e32 v8, v8
	v_sub_f32_e32 v17, v78, v36
	v_exp_f32_e32 v155, v17
	v_sub_f32_e32 v17, v81, v36
	v_add_f32_e32 v16, v8, v9
	v_sub_f32_e32 v9, v70, v36
	v_exp_f32_e32 v9, v9
	v_exp_f32_e32 v137, v17
	v_sub_f32_e32 v17, v80, v36
	v_exp_f32_e32 v140, v17
	v_add_f32_e32 v16, v9, v16
	v_add_f32_e32 v16, v148, v16
	v_add_f32_e32 v16, v149, v16
	v_add_f32_e32 v16, v150, v16
	v_add_f32_e32 v16, v151, v16
	v_add_f32_e32 v16, v152, v16
	v_add_f32_e32 v16, v153, v16
	v_sub_f32_e32 v17, v51, v36
	v_add_f32_e32 v16, v154, v16
	v_exp_f32_e32 v141, v17
	v_sub_f32_e32 v17, v50, v36
	v_add_f32_e32 v16, v155, v16
	v_exp_f32_e32 v143, v17
	v_sub_f32_e32 v17, v53, v36
	v_add_f32_e32 v16, v137, v16
	v_exp_f32_e32 v144, v17
	v_sub_f32_e32 v17, v52, v36
	v_add_f32_e32 v16, v140, v16
	v_exp_f32_e32 v145, v17
	v_sub_f32_e32 v17, v55, v36
	v_add_f32_e32 v16, v141, v16
	v_exp_f32_e32 v146, v17
	v_sub_f32_e32 v17, v54, v36
	v_add_f32_e32 v16, v143, v16
	v_exp_f32_e32 v147, v17
	v_sub_f32_e32 v17, v57, v36
	v_add_f32_e32 v16, v144, v16
	v_exp_f32_e32 v92, v17
	v_sub_f32_e32 v17, v56, v36
	v_add_f32_e32 v16, v145, v16
	v_exp_f32_e32 v93, v17
	v_sub_f32_e32 v17, v59, v36
	v_add_f32_e32 v16, v146, v16
	v_exp_f32_e32 v134, v17
	v_sub_f32_e32 v17, v58, v36
	v_add_f32_e32 v16, v147, v16
	v_exp_f32_e32 v135, v17
	v_sub_f32_e32 v17, v61, v36
	v_add_f32_e32 v16, v92, v16
	v_exp_f32_e32 v136, v17
	v_sub_f32_e32 v17, v60, v36
	v_add_f32_e32 v16, v93, v16
	v_exp_f32_e32 v138, v17
	v_sub_f32_e32 v17, v63, v36
	v_add_f32_e32 v16, v134, v16
	v_exp_f32_e32 v139, v17
	v_sub_f32_e32 v17, v62, v36
	v_add_f32_e32 v16, v135, v16
	v_exp_f32_e32 v142, v17
	v_sub_f32_e32 v17, v65, v36
	v_add_f32_e32 v16, v136, v16
	v_exp_f32_e32 v79, v17
	v_sub_f32_e32 v17, v64, v36
	v_add_f32_e32 v16, v138, v16
	v_exp_f32_e32 v83, v17
	v_sub_f32_e32 v17, v35, v36
	v_add_f32_e32 v16, v139, v16
	v_exp_f32_e32 v84, v17
	v_sub_f32_e32 v17, v34, v36
	v_add_f32_e32 v16, v142, v16
	v_exp_f32_e32 v86, v17
	v_sub_f32_e32 v17, v87, v36
	v_add_f32_e32 v16, v79, v16
	v_exp_f32_e32 v87, v17
	v_sub_f32_e32 v17, v88, v36
	v_add_f32_e32 v16, v83, v16
	v_exp_f32_e32 v88, v17
	v_sub_f32_e32 v17, v89, v36
	v_add_f32_e32 v16, v84, v16
	v_exp_f32_e32 v89, v17
	v_sub_f32_e32 v17, v39, v36
	v_add_f32_e32 v16, v86, v16
	v_exp_f32_e32 v90, v17
	v_sub_f32_e32 v17, v41, v36
	v_add_f32_e32 v16, v87, v16
	v_exp_f32_e32 v74, v17
	v_sub_f32_e32 v17, v40, v36
	v_add_f32_e32 v16, v88, v16
	v_exp_f32_e32 v75, v17
	v_sub_f32_e32 v17, v43, v36
	v_add_f32_e32 v16, v89, v16
	v_exp_f32_e32 v76, v17
	v_sub_f32_e32 v17, v42, v36
	v_add_f32_e32 v16, v90, v16
	v_exp_f32_e32 v77, v17
	v_sub_f32_e32 v17, v45, v36
	v_add_f32_e32 v16, v74, v16
	v_exp_f32_e32 v78, v17
	v_sub_f32_e32 v17, v44, v36
	v_add_f32_e32 v16, v75, v16
	v_exp_f32_e32 v80, v17
	v_sub_f32_e32 v17, v47, v36
	v_add_f32_e32 v16, v76, v16
	v_exp_f32_e32 v81, v17
	v_sub_f32_e32 v17, v46, v36
	v_add_f32_e32 v16, v77, v16
	v_exp_f32_e32 v85, v17
	v_sub_f32_e32 v17, v49, v36
	v_add_f32_e32 v16, v78, v16
	v_exp_f32_e32 v62, v17
	v_sub_f32_e32 v17, v48, v36
	v_add_f32_e32 v16, v80, v16
	v_exp_f32_e32 v65, v17
	v_sub_f32_e32 v17, v19, v36
	v_add_f32_e32 v16, v81, v16
	v_exp_f32_e32 v67, v17
	v_sub_f32_e32 v17, v18, v36
	v_add_f32_e32 v16, v85, v16
	v_exp_f32_e32 v69, v17
	v_sub_f32_e32 v17, v21, v36
; DI f32x16 zero16() { f32x16 z; for (int i = 0; i < 16; ++i) z[i] = 0.f; return z; }
; DI float ex2(float x) { return __builtin_amdgcn_exp2f(x); }
; DI void phase_mixb(const Prm& p, unsigned char* smem_raw, int S, int lgS, int& base) {
;     ...
; #pragma unroll
;     for (int tt = 0; tt < 5; ++tt)
; #pragma unroll
;       for (int r = 0; r < 16; ++r) {
;         const float pv = ex2(sc[tt][r] - mx);
;         sum += pv;
;         sc[tt][r] = pv;
;       }
;     sum += __shfl_xor(sum, 32);
;     f32x16 oacc[2];
;     oacc[0] = zero16(); oacc[1] = zero16();
; #pragma unroll
;     for (int tt = 0; tt < 5; ++tt) {
; #pragma unroll
;       for (int e = 0; e < 4; ++e) {
;         const int c = lane + 64 * e, key = c >> 3, dch = c & 7;
;         int ik = i0 - 64 + 32 * tt + key;
;         ik = min(max(ik, 0), L - 1);
;         const u32x4 raw = *(const u32x4*)(p.bqkv + (size_t)(tokbase + (ik << lgd)) * 1152 + 768 + hc + dch * 8);
	v_add_f32_e32 v16, v62, v16
	v_exp_f32_e32 v70, v17
	v_sub_f32_e32 v17, v20, v36
	v_add_f32_e32 v16, v65, v16
	v_exp_f32_e32 v71, v17
	v_sub_f32_e32 v17, v23, v36
	v_add_f32_e32 v16, v67, v16
	v_exp_f32_e32 v72, v17
	v_sub_f32_e32 v17, v22, v36
	v_add_f32_e32 v16, v69, v16
	v_exp_f32_e32 v73, v17
	v_sub_f32_e32 v17, v25, v36
	v_add_f32_e32 v16, v70, v16
	v_exp_f32_e32 v57, v17
	v_sub_f32_e32 v17, v24, v36
	v_add_f32_e32 v16, v71, v16
	v_exp_f32_e32 v58, v17
	v_sub_f32_e32 v17, v27, v36
	v_add_f32_e32 v16, v72, v16
	v_exp_f32_e32 v59, v17
	v_sub_f32_e32 v17, v26, v36
	v_add_f32_e32 v16, v73, v16
	v_exp_f32_e32 v60, v17
	v_sub_f32_e32 v17, v29, v36
	v_add_f32_e32 v16, v57, v16
	v_exp_f32_e32 v61, v17
	v_sub_f32_e32 v17, v28, v36
	v_add_f32_e32 v16, v58, v16
	v_exp_f32_e32 v63, v17
	v_sub_f32_e32 v17, v31, v36
	v_add_f32_e32 v16, v59, v16
	v_exp_f32_e32 v64, v17
	v_sub_f32_e32 v17, v30, v36
	v_add_f32_e32 v16, v60, v16
	v_exp_f32_e32 v68, v17
	v_sub_f32_e32 v17, v33, v36
	v_add_f32_e32 v16, v61, v16
	v_exp_f32_e32 v49, v17
	v_sub_f32_e32 v17, v32, v36
	v_add_f32_e32 v16, v63, v16
	v_exp_f32_e32 v50, v17
	v_sub_f32_e32 v17, v156, v36
	v_add_f32_e32 v16, v64, v16
	v_exp_f32_e32 v51, v17
	v_sub_f32_e32 v17, v91, v36
	v_add_f32_e32 v16, v68, v16
	v_exp_f32_e32 v52, v17
	v_sub_f32_e32 v17, v158, v36
	v_add_f32_e32 v16, v49, v16
	v_exp_f32_e32 v53, v17
	v_sub_f32_e32 v17, v157, v36
	v_add_f32_e32 v16, v50, v16
	v_exp_f32_e32 v54, v17
	v_sub_f32_e32 v17, v160, v36
	v_add_f32_e32 v16, v51, v16
	v_exp_f32_e32 v55, v17
	v_sub_f32_e32 v17, v159, v36
	v_add_f32_e32 v16, v52, v16
	v_exp_f32_e32 v56, v17
	v_sub_f32_e32 v17, v162, v36
	v_add_f32_e32 v16, v53, v16
	v_exp_f32_e32 v41, v17
	v_sub_f32_e32 v17, v161, v36
	v_add_f32_e32 v16, v54, v16
	v_exp_f32_e32 v42, v17
	v_sub_f32_e32 v11, v11, v36
	v_add_f32_e32 v16, v55, v16
	v_exp_f32_e32 v43, v11
	v_sub_f32_e32 v10, v10, v36
	v_add_f32_e32 v16, v56, v16
	v_exp_f32_e32 v44, v10
	v_add_f32_e32 v16, v41, v16
	v_add_f32_e32 v16, v42, v16
	v_add_f32_e32 v11, v43, v16
	v_add_f32_e32 v10, v44, v11
	v_sub_f32_e32 v11, v13, v36
	v_exp_f32_e32 v45, v11
	v_sub_f32_e32 v11, v12, v36
	v_exp_f32_e32 v46, v11
	v_sub_f32_e32 v11, v15, v36
	v_exp_f32_e32 v47, v11
	v_sub_f32_e32 v11, v14, v36
	v_exp_f32_e32 v48, v11
	v_add_f32_e32 v10, v45, v10
	v_add_f32_e32 v10, v46, v10
	v_add_f32_e32 v10, v47, v10
	v_add_f32_e32 v39, v48, v10
	v_mov_b64_e32 v[156:157], s[38:39]
	v_mov_b32_e32 v158, v96
	v_mov_b32_e32 v159, v1
	v_or_b32_e32 v40, v82, v108
	v_max_i32_e32 v40, 0, v40
	v_min_i32_e32 v40, v40, v132
	v_lshl_add_u32 v40, v40, v99, v131
	v_mad_i64_i32 v[14:15], s[2:3], v40, s4, v[156:157]
	v_lshl_add_u64 v[14:15], v[14:15], 0, v[102:103]
	v_lshl_add_u64 v[14:15], v[14:15], 0, v[158:159]
	global_load_dwordx4 v[160:163], v[14:15], off offset:1536
	v_or_b32_e32 v40, v82, v110
	v_max_i32_e32 v40, 0, v40
	v_min_i32_e32 v40, v40, v132
	v_lshl_add_u32 v40, v40, v99, v131
	v_mad_i64_i32 v[14:15], s[2:3], v40, s4, v[156:157]
	v_lshl_add_u64 v[14:15], v[14:15], 0, v[102:103]
	v_lshl_add_u64 v[14:15], v[14:15], 0, v[158:159]
	global_load_dwordx4 v[164:167], v[14:15], off offset:1536
	v_or_b32_e32 v40, v82, v111
	v_max_i32_e32 v40, 0, v40
	v_min_i32_e32 v40, v40, v132
	v_lshl_add_u32 v40, v40, v99, v131
	v_mad_i64_i32 v[14:15], s[2:3], v40, s4, v[156:157]
	v_lshl_add_u64 v[14:15], v[14:15], 0, v[102:103]
	v_lshl_add_u64 v[14:15], v[14:15], 0, v[158:159]
	global_load_dwordx4 v[168:171], v[14:15], off offset:1536
	v_or_b32_e32 v40, v82, v112
	v_max_i32_e32 v40, 0, v40
	v_min_i32_e32 v40, v40, v132
	v_lshl_add_u32 v40, v40, v99, v131
	v_mad_i64_i32 v[14:15], s[2:3], v40, s4, v[156:157]
	v_lshl_add_u64 v[14:15], v[14:15], 0, v[102:103]
	v_lshl_add_u64 v[14:15], v[14:15], 0, v[158:159]
	global_load_dwordx4 v[172:175], v[14:15], off offset:1536
	v_or_b32_e32 v40, v66, v108
	v_max_i32_e32 v40, 0, v40
	v_min_i32_e32 v40, v40, v132
	v_lshl_add_u32 v40, v40, v99, v131
	v_mad_i64_i32 v[14:15], s[2:3], v40, s4, v[156:157]
	v_lshl_add_u64 v[14:15], v[14:15], 0, v[102:103]
	v_lshl_add_u64 v[14:15], v[14:15], 0, v[158:159]
	global_load_dwordx4 v[176:179], v[14:15], off offset:1536
	v_or_b32_e32 v40, v66, v110
	v_max_i32_e32 v40, 0, v40
	v_min_i32_e32 v40, v40, v132
	v_lshl_add_u32 v40, v40, v99, v131
	v_mad_i64_i32 v[14:15], s[2:3], v40, s4, v[156:157]
	v_lshl_add_u64 v[14:15], v[14:15], 0, v[102:103]
	v_lshl_add_u64 v[14:15], v[14:15], 0, v[158:159]
	global_load_dwordx4 v[180:183], v[14:15], off offset:1536
	v_or_b32_e32 v40, v66, v111
	v_max_i32_e32 v40, 0, v40
	v_min_i32_e32 v40, v40, v132
	v_lshl_add_u32 v40, v40, v99, v131
	v_mad_i64_i32 v[14:15], s[2:3], v40, s4, v[156:157]
	v_lshl_add_u64 v[14:15], v[14:15], 0, v[102:103]
	v_lshl_add_u64 v[14:15], v[14:15], 0, v[158:159]
	global_load_dwordx4 v[184:187], v[14:15], off offset:1536
	v_or_b32_e32 v40, v66, v112
	v_max_i32_e32 v40, 0, v40
	v_min_i32_e32 v40, v40, v132
	v_lshl_add_u32 v40, v40, v99, v131
	v_mad_i64_i32 v[14:15], s[2:3], v40, s4, v[156:157]
	v_lshl_add_u64 v[14:15], v[14:15], 0, v[102:103]
	v_lshl_add_u64 v[14:15], v[14:15], 0, v[158:159]
	global_load_dwordx4 v[188:191], v[14:15], off offset:1536
	v_or_b32_e32 v40, v133, v108
	v_max_i32_e32 v40, 0, v40
	v_min_i32_e32 v40, v40, v132
	v_lshl_add_u32 v40, v40, v99, v131
	v_mad_i64_i32 v[14:15], s[2:3], v40, s4, v[156:157]
	v_lshl_add_u64 v[14:15], v[14:15], 0, v[102:103]
	v_lshl_add_u64 v[14:15], v[14:15], 0, v[158:159]
	global_load_dwordx4 v[192:195], v[14:15], off offset:1536
	v_or_b32_e32 v40, v133, v110
	v_max_i32_e32 v40, 0, v40
	v_min_i32_e32 v40, v40, v132
	v_lshl_add_u32 v40, v40, v99, v131
	v_mad_i64_i32 v[14:15], s[2:3], v40, s4, v[156:157]
; DI f32x16 mfma(bf16x8 a, bf16x8 b, f32x16 c) { return __builtin_amdgcn_mfma_f32_32x32x16_bf16(a, b, c, 0, 0, 0); }
; DI void phase_mixb(const Prm& p, unsigned char* smem_raw, int S, int lgS, int& base) {
;     ...
;     for (int tt = 0; tt < 5; ++tt) {
; #pragma unroll
;       for (int e = 0; e < 4; ++e) {
;         const int c = lane + 64 * e, key = c >> 3, dch = c & 7;
;         int ik = i0 - 64 + 32 * tt + key;
;         ik = min(max(ik, 0), L - 1);
;         const u32x4 raw = *(const u32x4*)(p.bqkv + (size_t)(tokbase + (ik << lgd)) * 1152 + 768 + hc + dch * 8);
; #pragma unroll
;         for (int jj = 0; jj < 4; ++jj) {
;           vt[(dch * 8 + 2 * jj) * 40 + key] = (u16)(raw[jj] & 0xffffu);
;           vt[(dch * 8 + 2 * jj + 1) * 40 + key] = (u16)(raw[jj] >> 16);
;         }
;       }
;       __syncthreads();
; #pragma unroll
;       for (int u = 0; u < 2; ++u) {
;         u32x4 pk;
; #pragma unroll
;         for (int jj = 0; jj < 4; ++jj) pk[jj] = pack2(sc[tt][8 * u + 2 * jj], sc[tt][8 * u + 2 * jj + 1]);
;         const bf16x8 pf = __builtin_bit_cast(bf16x8, pk);
; #pragma unroll
;         for (int dt = 0; dt < 2; ++dt) {
;           const u16* vp = vt + (dt * 32 + lr) * 40 + 16 * u + 4 * lh;
;           u32x4 vv;
;           const u32x2 lo = *(const u32x2*)vp, hi = *(const u32x2*)(vp + 8);
;           vv[0] = lo[0]; vv[1] = lo[1]; vv[2] = hi[0]; vv[3] = hi[1];
;           oacc[dt] = mfma(__builtin_bit_cast(bf16x8, vv), pf, oacc[dt]);
;         }
;       }
	v_lshl_add_u64 v[14:15], v[14:15], 0, v[102:103]
	v_lshl_add_u64 v[14:15], v[14:15], 0, v[158:159]
	global_load_dwordx4 v[196:199], v[14:15], off offset:1536
	v_or_b32_e32 v40, v133, v111
	v_max_i32_e32 v40, 0, v40
	v_min_i32_e32 v40, v40, v132
	v_lshl_add_u32 v40, v40, v99, v131
	v_mad_i64_i32 v[14:15], s[2:3], v40, s4, v[156:157]
	v_lshl_add_u64 v[14:15], v[14:15], 0, v[102:103]
	v_lshl_add_u64 v[14:15], v[14:15], 0, v[158:159]
	global_load_dwordx4 v[200:203], v[14:15], off offset:1536
	v_or_b32_e32 v40, v133, v112
	v_max_i32_e32 v40, 0, v40
	v_min_i32_e32 v40, v40, v132
	v_lshl_add_u32 v40, v40, v99, v131
	v_mad_i64_i32 v[14:15], s[2:3], v40, s4, v[156:157]
	v_lshl_add_u64 v[14:15], v[14:15], 0, v[102:103]
	v_lshl_add_u64 v[14:15], v[14:15], 0, v[158:159]
	global_load_dwordx4 v[204:207], v[14:15], off offset:1536
	v_or_b32_e32 v40, v38, v108
	v_max_i32_e32 v40, 0, v40
	v_min_i32_e32 v40, v40, v132
	v_lshl_add_u32 v40, v40, v99, v131
	v_mad_i64_i32 v[14:15], s[2:3], v40, s4, v[156:157]
	v_lshl_add_u64 v[14:15], v[14:15], 0, v[102:103]
	v_lshl_add_u64 v[14:15], v[14:15], 0, v[158:159]
	global_load_dwordx4 v[208:211], v[14:15], off offset:1536
	v_or_b32_e32 v40, v38, v110
	v_max_i32_e32 v40, 0, v40
	v_min_i32_e32 v40, v40, v132
	v_lshl_add_u32 v40, v40, v99, v131
	v_mad_i64_i32 v[14:15], s[2:3], v40, s4, v[156:157]
	v_lshl_add_u64 v[14:15], v[14:15], 0, v[102:103]
	v_lshl_add_u64 v[14:15], v[14:15], 0, v[158:159]
	global_load_dwordx4 v[212:215], v[14:15], off offset:1536
	v_or_b32_e32 v40, v38, v111
	v_max_i32_e32 v40, 0, v40
	v_min_i32_e32 v40, v40, v132
	v_lshl_add_u32 v40, v40, v99, v131
	v_mad_i64_i32 v[14:15], s[2:3], v40, s4, v[156:157]
	v_lshl_add_u64 v[14:15], v[14:15], 0, v[102:103]
	v_lshl_add_u64 v[14:15], v[14:15], 0, v[158:159]
	global_load_dwordx4 v[216:219], v[14:15], off offset:1536
	v_or_b32_e32 v40, v38, v112
	v_max_i32_e32 v40, 0, v40
	v_min_i32_e32 v40, v40, v132
	v_lshl_add_u32 v40, v40, v99, v131
	v_mad_i64_i32 v[14:15], s[2:3], v40, s4, v[156:157]
	v_lshl_add_u64 v[14:15], v[14:15], 0, v[102:103]
	v_lshl_add_u64 v[14:15], v[14:15], 0, v[158:159]
	global_load_dwordx4 v[220:223], v[14:15], off offset:1536
	v_or_b32_e32 v40, v37, v108
	v_max_i32_e32 v40, 0, v40
	v_min_i32_e32 v40, v40, v132
	v_lshl_add_u32 v40, v40, v99, v131
	v_mad_i64_i32 v[14:15], s[2:3], v40, s4, v[156:157]
	v_lshl_add_u64 v[14:15], v[14:15], 0, v[102:103]
	v_lshl_add_u64 v[14:15], v[14:15], 0, v[158:159]
	global_load_dwordx4 v[226:229], v[14:15], off offset:1536
	v_or_b32_e32 v40, v37, v110
	v_max_i32_e32 v40, 0, v40
	v_min_i32_e32 v40, v40, v132
	v_lshl_add_u32 v40, v40, v99, v131
	v_mad_i64_i32 v[14:15], s[2:3], v40, s4, v[156:157]
	v_lshl_add_u64 v[14:15], v[14:15], 0, v[102:103]
	v_lshl_add_u64 v[14:15], v[14:15], 0, v[158:159]
	global_load_dwordx4 v[234:237], v[14:15], off offset:1536
	v_or_b32_e32 v40, v37, v111
	v_max_i32_e32 v40, 0, v40
	v_min_i32_e32 v40, v40, v132
	v_lshl_add_u32 v40, v40, v99, v131
	v_mad_i64_i32 v[14:15], s[2:3], v40, s4, v[156:157]
	v_lshl_add_u64 v[14:15], v[14:15], 0, v[102:103]
	v_lshl_add_u64 v[14:15], v[14:15], 0, v[158:159]
	global_load_dwordx4 v[244:247], v[14:15], off offset:1536
	v_or_b32_e32 v40, v37, v112
	v_max_i32_e32 v40, 0, v40
	v_min_i32_e32 v40, v40, v132
	v_lshl_add_u32 v40, v40, v99, v131
	v_mad_i64_i32 v[14:15], s[2:3], v40, s4, v[156:157]
	v_lshl_add_u64 v[14:15], v[14:15], 0, v[102:103]
	v_lshl_add_u64 v[14:15], v[14:15], 0, v[158:159]
	global_load_dwordx4 v[248:251], v[14:15], off offset:1536
	v_mov_b64_e32 v[34:35], s[38:39]
	v_mov_b32_e32 v97, v1
	s_waitcnt vmcnt(19)
	ds_write_b16 v109, v160 offset:3328
	ds_write_b16_d16_hi v109, v160 offset:3408
	ds_write_b16 v109, v161 offset:3488
	ds_write_b16_d16_hi v109, v161 offset:3568
	ds_write_b16 v109, v162 offset:3648
	ds_write_b16_d16_hi v109, v162 offset:3728
	ds_write_b16 v109, v163 offset:3808
	ds_write_b16_d16_hi v109, v163 offset:3888
	s_waitcnt vmcnt(18)
	ds_write_b16 v109, v164 offset:3344
	ds_write_b16_d16_hi v109, v164 offset:3424
	ds_write_b16 v109, v165 offset:3504
	ds_write_b16_d16_hi v109, v165 offset:3584
	ds_write_b16 v109, v166 offset:3664
	ds_write_b16_d16_hi v109, v166 offset:3744
	ds_write_b16 v109, v167 offset:3824
	ds_write_b16_d16_hi v109, v167 offset:3904
	s_waitcnt vmcnt(17)
	ds_write_b16 v109, v168 offset:3360
	ds_write_b16_d16_hi v109, v168 offset:3440
	ds_write_b16 v109, v169 offset:3520
	ds_write_b16_d16_hi v109, v169 offset:3600
	ds_write_b16 v109, v170 offset:3680
	ds_write_b16_d16_hi v109, v170 offset:3760
	ds_write_b16 v109, v171 offset:3840
	ds_write_b16_d16_hi v109, v171 offset:3920
	v_add_u32_e32 v91, 0x800, v129
	s_waitcnt vmcnt(16)
	ds_write_b16 v109, v172 offset:3376
	ds_write_b16_d16_hi v109, v172 offset:3456
	ds_write_b16 v109, v173 offset:3536
	ds_write_b16_d16_hi v109, v173 offset:3616
	ds_write_b16 v109, v174 offset:3696
	ds_write_b16_d16_hi v109, v174 offset:3776
	ds_write_b16 v109, v175 offset:3856
	ds_write_b16_d16_hi v109, v175 offset:3936
	s_waitcnt lgkmcnt(0)
	s_nop 0
	v_cvt_pk_bf16_f32 v2, v2, v3
	v_cvt_pk_bf16_f32 v3, v4, v5
	v_cvt_pk_bf16_f32 v4, v6, v7
	v_cvt_pk_bf16_f32 v5, v8, v9
	ds_read2_b64 v[6:9], v91 offset0:160 offset1:162
	ds_read2_b64 v[156:159], v91 offset0:164 offset1:166
	v_add_u32_e32 v82, 0x1000, v129
	s_waitcnt lgkmcnt(1)
	v_mfma_f32_32x32x16_bf16 v[18:33], v[6:9], v[2:5], 0
	ds_read2_b64 v[6:9], v82 offset0:224 offset1:226
	v_cvt_pk_bf16_f32 v148, v148, v149
	v_cvt_pk_bf16_f32 v149, v150, v151
	v_cvt_pk_bf16_f32 v150, v152, v153
	v_cvt_pk_bf16_f32 v151, v154, v155
	ds_read2_b64 v[152:155], v82 offset0:228 offset1:230
	s_waitcnt lgkmcnt(0)
; DI f32x16 mfma(bf16x8 a, bf16x8 b, f32x16 c) { return __builtin_amdgcn_mfma_f32_32x32x16_bf16(a, b, c, 0, 0, 0); }
; DI void phase_mixb(const Prm& p, unsigned char* smem_raw, int S, int lgS, int& base) {
;     ...
;     for (int tt = 0; tt < 5; ++tt) {
; #pragma unroll
;       for (int e = 0; e < 4; ++e) {
;         const int c = lane + 64 * e, key = c >> 3, dch = c & 7;
;         int ik = i0 - 64 + 32 * tt + key;
;         ik = min(max(ik, 0), L - 1);
;         const u32x4 raw = *(const u32x4*)(p.bqkv + (size_t)(tokbase + (ik << lgd)) * 1152 + 768 + hc + dch * 8);
; #pragma unroll
;         for (int jj = 0; jj < 4; ++jj) {
;           vt[(dch * 8 + 2 * jj) * 40 + key] = (u16)(raw[jj] & 0xffffu);
;           vt[(dch * 8 + 2 * jj + 1) * 40 + key] = (u16)(raw[jj] >> 16);
;         }
;       }
;       __syncthreads();
; #pragma unroll
;       for (int u = 0; u < 2; ++u) {
;         u32x4 pk;
; #pragma unroll
;         for (int jj = 0; jj < 4; ++jj) pk[jj] = pack2(sc[tt][8 * u + 2 * jj], sc[tt][8 * u + 2 * jj + 1]);
;         const bf16x8 pf = __builtin_bit_cast(bf16x8, pk);
; #pragma unroll
;         for (int dt = 0; dt < 2; ++dt) {
;           const u16* vp = vt + (dt * 32 + lr) * 40 + 16 * u + 4 * lh;
;           u32x4 vv;
;           const u32x2 lo = *(const u32x2*)vp, hi = *(const u32x2*)(vp + 8);
;           vv[0] = lo[0]; vv[1] = lo[1]; vv[2] = hi[0]; vv[3] = hi[1];
;           oacc[dt] = mfma(__builtin_bit_cast(bf16x8, vv), pf, oacc[dt]);
;         }
;       }
;       __syncthreads();
	v_mfma_f32_32x32x16_bf16 v[2:17], v[6:9], v[2:5], 0
	s_nop 0
	v_cvt_pk_bf16_f32 v74, v74, v75
	v_cvt_pk_bf16_f32 v75, v76, v77
	v_cvt_pk_bf16_f32 v76, v78, v80
	v_cvt_pk_bf16_f32 v77, v81, v85
	v_cvt_pk_bf16_f32 v59, v59, v60
	v_mfma_f32_32x32x16_bf16 v[18:33], v[156:159], v[148:151], v[18:33]
	v_cvt_pk_bf16_f32 v60, v61, v63
	v_cvt_pk_bf16_f32 v61, v64, v68
	v_cvt_pk_bf16_f32 v58, v57, v58
	v_cvt_pk_bf16_f32 v51, v51, v52
	v_cvt_pk_bf16_f32 v52, v53, v54
	v_cvt_pk_bf16_f32 v53, v55, v56
	v_cvt_pk_bf16_f32 v50, v49, v50
	v_mfma_f32_32x32x16_bf16 v[2:17], v[152:155], v[148:151], v[2:17]
	s_waitcnt vmcnt(15)
	ds_write_b16 v109, v176 offset:3328
	ds_write_b16_d16_hi v109, v176 offset:3408
	ds_write_b16 v109, v177 offset:3488
	ds_write_b16_d16_hi v109, v177 offset:3568
	ds_write_b16 v109, v178 offset:3648
	ds_write_b16_d16_hi v109, v178 offset:3728
	ds_write_b16 v109, v179 offset:3808
	ds_write_b16_d16_hi v109, v179 offset:3888
	s_waitcnt vmcnt(14)
	ds_write_b16 v109, v180 offset:3344
	ds_write_b16_d16_hi v109, v180 offset:3424
	ds_write_b16 v109, v181 offset:3504
	ds_write_b16_d16_hi v109, v181 offset:3584
	ds_write_b16 v109, v182 offset:3664
	ds_write_b16_d16_hi v109, v182 offset:3744
	ds_write_b16 v109, v183 offset:3824
	ds_write_b16_d16_hi v109, v183 offset:3904
	s_waitcnt vmcnt(13)
	ds_write_b16 v109, v184 offset:3360
	ds_write_b16_d16_hi v109, v184 offset:3440
	ds_write_b16 v109, v185 offset:3520
	ds_write_b16_d16_hi v109, v185 offset:3600
	ds_write_b16 v109, v186 offset:3680
	ds_write_b16_d16_hi v109, v186 offset:3760
	ds_write_b16 v109, v187 offset:3840
	ds_write_b16_d16_hi v109, v187 offset:3920
	s_waitcnt vmcnt(12)
	ds_write_b16 v109, v188 offset:3376
	ds_write_b16_d16_hi v109, v188 offset:3456
	ds_write_b16 v109, v189 offset:3536
	ds_write_b16_d16_hi v109, v189 offset:3616
	ds_write_b16 v109, v190 offset:3696
	ds_write_b16_d16_hi v109, v190 offset:3776
	ds_write_b16 v109, v191 offset:3856
	ds_write_b16_d16_hi v109, v191 offset:3936
	s_waitcnt lgkmcnt(0)
	s_nop 0
	v_cvt_pk_bf16_f32 v150, v144, v145
	v_cvt_pk_bf16_f32 v151, v146, v147
	ds_read2_b64 v[144:147], v91 offset0:160 offset1:162
	ds_read2_b64 v[152:155], v91 offset0:164 offset1:166
	v_cvt_pk_bf16_f32 v148, v137, v140
	v_cvt_pk_bf16_f32 v149, v141, v143
	s_waitcnt lgkmcnt(1)
	s_nop 0
	v_mfma_f32_32x32x16_bf16 v[18:33], v[144:147], v[148:151], v[18:33]
	ds_read2_b64 v[144:147], v82 offset0:224 offset1:226
	ds_bpermute_b32 v40, v106, v39
	v_cvt_pk_bf16_f32 v43, v43, v44
	v_cvt_pk_bf16_f32 v44, v45, v46
	v_cvt_pk_bf16_f32 v45, v47, v48
	v_cvt_pk_bf16_f32 v42, v41, v42
	s_waitcnt lgkmcnt(1)
	v_mfma_f32_32x32x16_bf16 v[2:17], v[144:147], v[148:151], v[2:17]
	v_cvt_pk_bf16_f32 v145, v134, v135
	v_cvt_pk_bf16_f32 v146, v136, v138
	ds_read2_b64 v[134:137], v82 offset0:228 offset1:230
	v_cvt_pk_bf16_f32 v144, v92, v93
	v_cvt_pk_bf16_f32 v147, v139, v142
	s_waitcnt lgkmcnt(0)
	s_nop 0
	v_mfma_f32_32x32x16_bf16 v[2:17], v[134:137], v[144:147], v[2:17]
	s_nop 0
	s_waitcnt vmcnt(11)
	ds_write_b16 v109, v192 offset:3328
	ds_write_b16_d16_hi v109, v192 offset:3408
	ds_write_b16 v109, v193 offset:3488
	ds_write_b16_d16_hi v109, v193 offset:3568
	ds_write_b16 v109, v194 offset:3648
	ds_write_b16_d16_hi v109, v194 offset:3728
	ds_write_b16 v109, v195 offset:3808
	ds_write_b16_d16_hi v109, v195 offset:3888
	s_waitcnt vmcnt(10)
	ds_write_b16 v109, v196 offset:3344
	ds_write_b16_d16_hi v109, v196 offset:3424
	ds_write_b16 v109, v197 offset:3504
	ds_write_b16_d16_hi v109, v197 offset:3584
	ds_write_b16 v109, v198 offset:3664
	ds_write_b16_d16_hi v109, v198 offset:3744
	ds_write_b16 v109, v199 offset:3824
	ds_write_b16_d16_hi v109, v199 offset:3904
	s_waitcnt vmcnt(9)
	ds_write_b16 v109, v200 offset:3360
	ds_write_b16_d16_hi v109, v200 offset:3440
	ds_write_b16 v109, v201 offset:3520
	ds_write_b16_d16_hi v109, v201 offset:3600
	ds_write_b16 v109, v202 offset:3680
	ds_write_b16_d16_hi v109, v202 offset:3760
	ds_write_b16 v109, v203 offset:3840
	ds_write_b16_d16_hi v109, v203 offset:3920
	v_mfma_f32_32x32x16_bf16 v[18:33], v[152:155], v[144:147], v[18:33]
	s_waitcnt vmcnt(8)
	ds_write_b16 v109, v204 offset:3376
	ds_write_b16_d16_hi v109, v204 offset:3456
	ds_write_b16 v109, v205 offset:3536
	ds_write_b16_d16_hi v109, v205 offset:3616
	ds_write_b16 v109, v206 offset:3696
	ds_write_b16_d16_hi v109, v206 offset:3776
	ds_write_b16 v109, v207 offset:3856
	ds_write_b16_d16_hi v109, v207 offset:3936
	s_waitcnt lgkmcnt(0)
	s_nop 0
	v_cvt_pk_bf16_f32 v135, v84, v86
	v_cvt_pk_bf16_f32 v136, v87, v88
	v_cvt_pk_bf16_f32 v137, v89, v90
	ds_read2_b64 v[86:89], v91 offset0:160 offset1:162
	ds_read2_b64 v[138:141], v91 offset0:164 offset1:166
	v_cvt_pk_bf16_f32 v134, v79, v83
	ds_read2_b64 v[78:81], v82 offset0:228 offset1:230
	s_waitcnt lgkmcnt(2)
	v_mfma_f32_32x32x16_bf16 v[18:33], v[86:89], v[134:137], v[18:33]
	ds_read2_b64 v[86:89], v82 offset0:224 offset1:226
	s_waitcnt lgkmcnt(0)
	s_nop 0
	v_readlane_b32 s37, v253, 25
	v_mfma_f32_32x32x16_bf16 v[2:17], v[86:89], v[134:137], v[2:17]
	v_readlane_b32 s40, v253, 28
	v_readlane_b32 s41, v253, 29
	v_readlane_b32 s42, v253, 30
	v_readlane_b32 s43, v253, 31
	v_readlane_b32 s44, v253, 32
	v_readlane_b32 s45, v253, 33
	v_readlane_b32 s46, v253, 34
	v_mfma_f32_32x32x16_bf16 v[18:33], v[138:141], v[74:77], v[18:33]
	v_readlane_b32 s47, v253, 35
	v_readlane_b32 s48, v253, 36
	v_readlane_b32 s49, v253, 37
	v_readlane_b32 s50, v253, 38
	v_readlane_b32 s51, v253, 39
	v_mfma_f32_32x32x16_bf16 v[2:17], v[78:81], v[74:77], v[2:17]
	s_waitcnt vmcnt(7)
; DI f32x16 mfma(bf16x8 a, bf16x8 b, f32x16 c) { return __builtin_amdgcn_mfma_f32_32x32x16_bf16(a, b, c, 0, 0, 0); }
; DI void phase_mixb(const Prm& p, unsigned char* smem_raw, int S, int lgS, int& base) {
;     ...
;     for (int tt = 0; tt < 5; ++tt) {
; #pragma unroll
;       for (int e = 0; e < 4; ++e) {
;         const int c = lane + 64 * e, key = c >> 3, dch = c & 7;
;         int ik = i0 - 64 + 32 * tt + key;
;         ik = min(max(ik, 0), L - 1);
;         const u32x4 raw = *(const u32x4*)(p.bqkv + (size_t)(tokbase + (ik << lgd)) * 1152 + 768 + hc + dch * 8);
; #pragma unroll
;         for (int jj = 0; jj < 4; ++jj) {
;           vt[(dch * 8 + 2 * jj) * 40 + key] = (u16)(raw[jj] & 0xffffu);
;           vt[(dch * 8 + 2 * jj + 1) * 40 + key] = (u16)(raw[jj] >> 16);
;         }
;       }
;       __syncthreads();
; #pragma unroll
;       for (int u = 0; u < 2; ++u) {
;         u32x4 pk;
; #pragma unroll
;         for (int jj = 0; jj < 4; ++jj) pk[jj] = pack2(sc[tt][8 * u + 2 * jj], sc[tt][8 * u + 2 * jj + 1]);
;         const bf16x8 pf = __builtin_bit_cast(bf16x8, pk);
; #pragma unroll
;         for (int dt = 0; dt < 2; ++dt) {
;           const u16* vp = vt + (dt * 32 + lr) * 40 + 16 * u + 4 * lh;
;           u32x4 vv;
;           const u32x2 lo = *(const u32x2*)vp, hi = *(const u32x2*)(vp + 8);
;           vv[0] = lo[0]; vv[1] = lo[1]; vv[2] = hi[0]; vv[3] = hi[1];
;           oacc[dt] = mfma(__builtin_bit_cast(bf16x8, vv), pf, oacc[dt]);
;         }
;       }
;       __syncthreads();
;     }
;     const float inv = 1.f / sum;
; #pragma unroll
;     for (int dt = 0; dt < 2; ++dt)
; #pragma unroll
;       for (int q = 0; q < 4; ++q) {
;         float4 o;
;         o.x = oacc[dt][4 * q] * inv; o.y = oacc[dt][4 * q + 1] * inv; o.z = oacc[dt][4 * q + 2] * inv; o.w = oacc[dt][4 * q + 3] * inv;
;         *(float4*)(p.og + (size_t)qtok * 384 + hc + dt * 32 + 8 * q + 4 * lh) = o;
;       }
;     if (lh == 0) p.lse[(size_t)qtok * 6 + hd] = (mx + __log2f(sum)) * LN2;
	ds_write_b16 v109, v208 offset:3328
	ds_write_b16_d16_hi v109, v208 offset:3408
	ds_write_b16 v109, v209 offset:3488
	ds_write_b16_d16_hi v109, v209 offset:3568
	ds_write_b16 v109, v210 offset:3648
	ds_write_b16_d16_hi v109, v210 offset:3728
	ds_write_b16 v109, v211 offset:3808
	ds_write_b16_d16_hi v109, v211 offset:3888
	s_waitcnt vmcnt(6)
	ds_write_b16 v109, v212 offset:3344
	ds_write_b16_d16_hi v109, v212 offset:3424
	ds_write_b16 v109, v213 offset:3504
	ds_write_b16_d16_hi v109, v213 offset:3584
	ds_write_b16 v109, v214 offset:3664
	ds_write_b16_d16_hi v109, v214 offset:3744
	ds_write_b16 v109, v215 offset:3824
	ds_write_b16_d16_hi v109, v215 offset:3904
	s_waitcnt vmcnt(5)
	ds_write_b16 v109, v216 offset:3360
	ds_write_b16_d16_hi v109, v216 offset:3440
	ds_write_b16 v109, v217 offset:3520
	ds_write_b16_d16_hi v109, v217 offset:3600
	ds_write_b16 v109, v218 offset:3680
	ds_write_b16_d16_hi v109, v218 offset:3760
	ds_write_b16 v109, v219 offset:3840
	ds_write_b16_d16_hi v109, v219 offset:3920
	s_waitcnt vmcnt(4)
	ds_write_b16 v109, v220 offset:3376
	ds_write_b16_d16_hi v109, v220 offset:3456
	ds_write_b16 v109, v221 offset:3536
	ds_write_b16_d16_hi v109, v221 offset:3616
	ds_write_b16 v109, v222 offset:3696
	ds_write_b16_d16_hi v109, v222 offset:3776
	ds_write_b16 v109, v223 offset:3856
	ds_write_b16_d16_hi v109, v223 offset:3936
	s_waitcnt lgkmcnt(0)
	s_nop 0
	v_cvt_pk_bf16_f32 v76, v70, v71
	v_cvt_pk_bf16_f32 v77, v72, v73
	ds_read2_b64 v[70:73], v91 offset0:160 offset1:162
	ds_read2_b64 v[78:81], v91 offset0:164 offset1:166
	v_cvt_pk_bf16_f32 v74, v62, v65
	v_cvt_pk_bf16_f32 v75, v67, v69
	ds_read2_b64 v[62:65], v82 offset0:228 offset1:230
	s_waitcnt lgkmcnt(2)
	v_mfma_f32_32x32x16_bf16 v[18:33], v[70:73], v[74:77], v[18:33]
	ds_read2_b64 v[70:73], v82 offset0:224 offset1:226
	s_waitcnt lgkmcnt(0)
	s_nop 0
	v_mfma_f32_32x32x16_bf16 v[2:17], v[70:73], v[74:77], v[2:17]
	v_mfma_f32_32x32x16_bf16 v[18:33], v[78:81], v[58:61], v[18:33]
	v_mfma_f32_32x32x16_bf16 v[2:17], v[62:65], v[58:61], v[2:17]
	s_waitcnt vmcnt(3)
	ds_write_b16 v109, v226 offset:3328
	ds_write_b16_d16_hi v109, v226 offset:3408
	ds_write_b16 v109, v227 offset:3488
	ds_write_b16_d16_hi v109, v227 offset:3568
	ds_write_b16 v109, v228 offset:3648
	ds_write_b16_d16_hi v109, v228 offset:3728
	ds_write_b16 v109, v229 offset:3808
	ds_write_b16_d16_hi v109, v229 offset:3888
	s_waitcnt vmcnt(2)
	ds_write_b16 v109, v234 offset:3344
	ds_write_b16_d16_hi v109, v234 offset:3424
	ds_write_b16 v109, v235 offset:3504
	ds_write_b16_d16_hi v109, v235 offset:3584
	ds_write_b16 v109, v236 offset:3664
	ds_write_b16_d16_hi v109, v236 offset:3744
	ds_write_b16 v109, v237 offset:3824
	ds_write_b16_d16_hi v109, v237 offset:3904
	s_waitcnt vmcnt(1)
	ds_write_b16 v109, v244 offset:3360
	ds_write_b16_d16_hi v109, v244 offset:3440
	ds_write_b16 v109, v245 offset:3520
	ds_write_b16_d16_hi v109, v245 offset:3600
	ds_write_b16 v109, v246 offset:3680
	ds_write_b16_d16_hi v109, v246 offset:3760
	ds_write_b16 v109, v247 offset:3840
	ds_write_b16_d16_hi v109, v247 offset:3920
	s_waitcnt vmcnt(0)
	ds_write_b16 v109, v248 offset:3376
	ds_write_b16_d16_hi v109, v248 offset:3456
	ds_write_b16 v109, v249 offset:3536
	ds_write_b16_d16_hi v109, v249 offset:3616
	ds_write_b16 v109, v250 offset:3696
	ds_write_b16_d16_hi v109, v250 offset:3776
	ds_write_b16 v109, v251 offset:3856
	ds_write_b16_d16_hi v109, v251 offset:3936
	s_waitcnt lgkmcnt(0)
	s_nop 0
	ds_read2_b64 v[54:57], v91 offset0:160 offset1:162
	ds_read2_b64 v[58:61], v91 offset0:164 offset1:166
	s_waitcnt lgkmcnt(1)
	v_mfma_f32_32x32x16_bf16 v[18:33], v[54:57], v[50:53], v[18:33]
	ds_read2_b64 v[54:57], v82 offset0:224 offset1:226
	ds_read2_b64 v[46:49], v82 offset0:228 offset1:230
	v_add_f32_e32 v34, v39, v40
	v_div_scale_f32 v35, s[2:3], v34, v34, 1.0
	v_rcp_f32_e32 v37, v35
	s_waitcnt lgkmcnt(0)
	v_mfma_f32_32x32x16_bf16 v[2:17], v[54:57], v[50:53], v[2:17]
	v_fma_f32 v38, -v35, v37, 1.0
	v_fmac_f32_e32 v37, v38, v37
	v_div_scale_f32 v38, vcc, 1.0, v34, 1.0
	v_mul_f32_e32 v39, v38, v37
	v_fma_f32 v40, -v35, v39, v38
	v_fmac_f32_e32 v39, v40, v37
	v_mfma_f32_32x32x16_bf16 v[18:33], v[58:61], v[42:45], v[18:33]
	v_fma_f32 v35, -v35, v39, v38
	v_mov_b64_e32 v[40:41], s[24:25]
	v_div_fmas_f32 v35, v35, v37, v39
	v_mad_i64_i32 v[40:41], s[2:3], v130, s83, v[40:41]
	v_div_fixup_f32 v38, v35, v34, 1.0
	v_lshl_add_u64 v[40:41], v[100:101], 2, v[40:41]
	v_mfma_f32_32x32x16_bf16 v[2:17], v[46:49], v[42:45], v[2:17]
	v_lshlrev_b32_e32 v42, 2, v94
	v_mov_b32_e32 v43, v1
	v_lshl_add_u64 v[40:41], v[40:41], 0, v[42:43]
	s_nop 1
	v_mul_f32_e64 v18, v38, v18
	v_mul_f32_e64 v19, v38, v19
	v_pk_mul_f32 v[20:21], v[38:39], v[20:21] op_sel_hi:[0,1]
	s_nop 0
	s_nop 2
	v_pk_mul_f32 v[2:3], v[38:39], v[2:3] op_sel_hi:[0,1]
	v_pk_mul_f32 v[4:5], v[38:39], v[4:5] op_sel_hi:[0,1]
	global_store_dwordx4 v[40:41], v[18:21], off
	global_store_dwordx4 v[40:41], v[2:5], off offset:128
	s_nop 0
	v_pk_mul_f32 v[18:19], v[38:39], v[22:23] op_sel_hi:[0,1]
	v_pk_mul_f32 v[20:21], v[38:39], v[24:25] op_sel_hi:[0,1]
	v_pk_mul_f32 v[2:3], v[38:39], v[6:7] op_sel_hi:[0,1]
	v_pk_mul_f32 v[4:5], v[38:39], v[8:9] op_sel_hi:[0,1]
	global_store_dwordx4 v[40:41], v[18:21], off offset:32
	global_store_dwordx4 v[40:41], v[2:5], off offset:160
	s_nop 0
	v_pk_mul_f32 v[18:19], v[38:39], v[26:27] op_sel_hi:[0,1]
	v_pk_mul_f32 v[20:21], v[38:39], v[28:29] op_sel_hi:[0,1]
	v_pk_mul_f32 v[2:3], v[38:39], v[10:11] op_sel_hi:[0,1]
	v_pk_mul_f32 v[4:5], v[38:39], v[12:13] op_sel_hi:[0,1]
	global_store_dwordx4 v[40:41], v[18:21], off offset:64
	global_store_dwordx4 v[40:41], v[2:5], off offset:192
	s_nop 0
	v_pk_mul_f32 v[18:19], v[38:39], v[30:31] op_sel_hi:[0,1]
	v_pk_mul_f32 v[20:21], v[38:39], v[32:33] op_sel_hi:[0,1]
	v_pk_mul_f32 v[2:3], v[38:39], v[14:15] op_sel_hi:[0,1]
	v_pk_mul_f32 v[4:5], v[38:39], v[16:17] op_sel_hi:[0,1]
	global_store_dwordx4 v[40:41], v[18:21], off offset:96
	global_store_dwordx4 v[40:41], v[2:5], off offset:224
	s_and_saveexec_b64 s[2:3], s[0:1]
	s_cbranch_execz .LBB0_1836
	v_log_f32_e32 v4, v34
	v_ashrrev_i32_e32 v99, 31, v98
	v_mad_i64_i32 v[2:3], s[4:5], v130, 24, s[26:27]
	v_add_f32_e32 v4, v36, v4
	v_mul_f32_e32 v4, 0x3f317218, v4
	v_lshl_add_u64 v[2:3], v[98:99], 2, v[2:3]
	global_store_dword v[2:3], v4, off
	s_branch .LBB0_1836
